# dilated item epilogue: 8 dwordx2 row stores widened to 4 dwordx4 via v_permlane32_swap pairs (T21); on top of subln load hoist
# speedup vs baseline: 1.0002x; 1.0002x over previous
; DI unsigned pack2(float a, float b) { f2_t v = {a, b}; return __builtin_bit_cast(unsigned, __builtin_convertvector(v, bf2_t)); }
; DI void local_store_out(const f32x16 (&O)[2], float l_run, u16* op, int hh) {
;   const float l = l_run + __shfl_xor(l_run, 32);
;   const float il = 1.f / l;
; #pragma unroll
;   for (int mb = 0; mb < 2; ++mb)
; #pragma unroll
;     for (int g = 0; g < 4; ++g) {
;       const int d = mb * 32 + 8 * g + 4 * hh;
;       *(uint2*)(op + d) = make_uint2(pack2(O[mb][4 * g] * il, O[mb][4 * g + 1] * il), pack2(O[mb][4 * g + 2] * il, O[mb][4 * g + 3] * il));
;     }
; }
; DI void swin_attn_item(KP p, int item, u16* sm) {
;     ...
;   const size_t orow = (size_t)pat * NTOK + (size_t)b * S + tq;
;   const float l = l_run + __shfl_xor(l_run, 32);
;   if (hh == 0) p.lse[orow * 6 + head] = m_run + __log2f(l);
;   local_store_out(O, l_run, p.odil + orow * 384 + head * 64, hh);
.Ldil_c_done:
	s_nop 7
	ds_bpermute_b32 v0, v12, v5
	s_lshl_b32 s12, s38, 15
	s_lshl_b32 s16, s39, 14
	s_add_i32 s12, s12, s16
	v_add_u32_e32 v15, s12, v15
	s_waitcnt lgkmcnt(0)
	v_add_f32_e32 v5, v5, v0
	v_log_f32_e32 v14, v5
	v_mov_b32_e32 v186, s30
	v_mov_b32_e32 v187, s31
	v_mad_u64_u32 v[188:189], s[18:19], v15, 24, v[186:187]
	s_lshl_b32 s12, s40, 2
	v_lshl_add_u64 v[188:189], v[188:189], 0, s[12:13]
	v_add_f32_e32 v14, v4, v14
	v_cmp_eq_u32_e32 vcc, 0, v3
	s_and_saveexec_b64 s[20:21], vcc
	global_store_dword v[188:189], v14, off
	s_mov_b64 exec, s[20:21]
	v_div_scale_f32 v184, s[18:19], v5, v5, 1.0
	v_rcp_f32_e32 v185, v184
	s_nop 0
	v_fma_f32 v188, -v184, v185, 1.0
	v_fmac_f32_e32 v185, v188, v185
	v_div_scale_f32 v188, vcc, 1.0, v5, 1.0
	v_mul_f32_e32 v189, v188, v185
	v_fma_f32 v0, -v184, v189, v188
	v_fmac_f32_e32 v189, v0, v185
	v_fma_f32 v184, -v184, v189, v188
	v_div_fmas_f32 v184, v184, v185, v189
	v_div_fixup_f32 v0, v184, v5, 1.0
	v_mov_b32_e32 v186, s34
	v_mov_b32_e32 v187, s35
	s_movk_i32 s12, 0x300
	v_mad_u64_u32 v[188:189], s[18:19], v15, s12, v[186:187]
	s_lshl_b32 s12, s40, 7
	v_lshl_add_u64 v[188:189], v[188:189], 0, s[12:13]
	v_lshlrev_b32_e32 v186, 4, v3
	v_mov_b32_e32 v187, 0
	v_lshl_add_u64 v[188:189], v[188:189], 0, v[186:187]
	v_mul_f32_e32 v32, v32, v0
	v_mul_f32_e32 v33, v33, v0
	v_mul_f32_e32 v34, v34, v0
	v_mul_f32_e32 v35, v35, v0
	v_mul_f32_e32 v36, v36, v0
	v_mul_f32_e32 v37, v37, v0
	v_mul_f32_e32 v38, v38, v0
	v_mul_f32_e32 v39, v39, v0
	v_mul_f32_e32 v40, v40, v0
	v_mul_f32_e32 v41, v41, v0
	v_mul_f32_e32 v42, v42, v0
	v_mul_f32_e32 v43, v43, v0
	v_mul_f32_e32 v44, v44, v0
	v_mul_f32_e32 v45, v45, v0
	v_mul_f32_e32 v46, v46, v0
	v_mul_f32_e32 v47, v47, v0
	v_mul_f32_e32 v48, v48, v0
	v_mul_f32_e32 v49, v49, v0
	v_mul_f32_e32 v50, v50, v0
	v_mul_f32_e32 v51, v51, v0
	v_mul_f32_e32 v52, v52, v0
	v_mul_f32_e32 v53, v53, v0
	v_mul_f32_e32 v54, v54, v0
	v_mul_f32_e32 v55, v55, v0
	v_mul_f32_e32 v56, v56, v0
	v_mul_f32_e32 v57, v57, v0
	v_mul_f32_e32 v58, v58, v0
	v_mul_f32_e32 v59, v59, v0
	v_mul_f32_e32 v60, v60, v0
	v_mul_f32_e32 v61, v61, v0
	v_mul_f32_e32 v62, v62, v0
	v_mul_f32_e32 v63, v63, v0
	v_cvt_pk_bf16_f32 v64, v32, v33
	v_cvt_pk_bf16_f32 v65, v34, v35
	v_cvt_pk_bf16_f32 v66, v36, v37
	v_cvt_pk_bf16_f32 v67, v38, v39
	v_cvt_pk_bf16_f32 v68, v40, v41
	v_cvt_pk_bf16_f32 v69, v42, v43
	v_cvt_pk_bf16_f32 v70, v44, v45
	v_cvt_pk_bf16_f32 v71, v46, v47
	v_cvt_pk_bf16_f32 v72, v48, v49
	v_cvt_pk_bf16_f32 v73, v50, v51
	v_cvt_pk_bf16_f32 v74, v52, v53
	v_cvt_pk_bf16_f32 v75, v54, v55
	v_cvt_pk_bf16_f32 v76, v56, v57
	v_cvt_pk_bf16_f32 v77, v58, v59
	v_cvt_pk_bf16_f32 v78, v60, v61
	v_cvt_pk_bf16_f32 v79, v62, v63
	s_nop 1
	v_permlane32_swap_b32_e32 v64, v66
	v_permlane32_swap_b32_e32 v65, v67
	v_permlane32_swap_b32_e32 v68, v70
	v_permlane32_swap_b32_e32 v69, v71
	v_permlane32_swap_b32_e32 v72, v74
	v_permlane32_swap_b32_e32 v73, v75
	v_permlane32_swap_b32_e32 v76, v78
	v_permlane32_swap_b32_e32 v77, v79
	global_store_dwordx4 v[188:189], v[64:67], off
	global_store_dwordx4 v[188:189], v[68:71], off offset:32
	global_store_dwordx4 v[188:189], v[72:75], off offset:64
	global_store_dwordx4 v[188:189], v[76:79], off offset:96
	s_branch .LBB0_263
